# v19 plus removal of four never-taken execz branches in NSA compressed pass 2 (size compensated)
# baseline (speedup 1.0000x reference)
; DI float fexp2(float x) { return __builtin_amdgcn_exp2f(x); }
; DI void nsa_block(const bf16_t* P1, const bf16_t* VT1, const bf16_t* KSF, const bf16_t* KC, const bf16_t* VCT, bf16_t* O, const unsigned* kmx, int b, int g, int t0b, int wave, int lane, unsigned char* lds) {
;     ...
;         if (it >= lo_w && it < ntile) {
;         const int ib = 32 * it;
;         f32x16 s = qk_lds(B, qf, krow, hf);
; #pragma unroll
;         for (int j = 0; j < 16; ++j) { const int dist = t - 31 - 16 * (ib + 16 * (j >> 3) + 8 * hf + (j & 7)); s[j] = dist >= 0 ? fexp2(s[j] * C1 - slope2 * (float)dist - m) * inv : 0.f; }
; #pragma unroll
;         for (int q = 0; q < 4; ++q) {
;             float gsum = (s[4 * q] + s[4 * q + 1]) + (s[4 * q + 2] + s[4 * q + 3]), e = s[4 * q + 3];
;             gsum += __shfl_xor(gsum, 1); gsum += __shfl_xor(gsum, 2); e += __shfl_xor(e, 1); e += __shfl_xor(e, 2);
;             const int ssel = (ib >> 2) + 4 * (q >> 1) + 2 * hf + (q & 1);
;             if (hh == 0) { impA[tk * 128 + ssel] = gsum; if (ssel + 1 < 128) impB[tk * 128 + ssel + 1] = e; }
.LBB0_1001:
	s_or_b64 exec, exec, s[2:3]
	v_cmp_ge_i32_e64 s[0:1], v32, v64
	v_cmp_lt_i32_e64 s[10:11], v32, v66
	s_and_b64 s[0:1], s[0:1], s[10:11]
	s_and_saveexec_b64 s[2:3], s[0:1]
	s_cbranch_execz .LBB0_1013
	v_and_b32_e32 v32, 1, v57
	v_cmp_eq_u32_e64 s[0:1], 1, v32
	v_sub_u32_e32 v81, v54, v58
	v_cvt_f32_u32_e32 v151, v81
	v_cndmask_b32_e64 v32, 0, v193, s[0:1]
	v_add_u32_e32 v71, s95, v32
	v_add3_u32 v76, v71, v174, v175
	ds_read_b128 v[32:35], v76
	ds_read_b128 v[72:75], v76 offset:32
	v_sub_u32_e32 v80, v53, v58
	s_waitcnt lgkmcnt(1)
	v_mfma_f32_32x32x16_bf16 v[32:47], v[32:35], v[112:115], 0
	s_waitcnt lgkmcnt(0)
	v_mfma_f32_32x32x16_bf16 v[32:47], v[72:75], v[116:119], v[32:47]
	ds_read_b128 v[72:75], v76 offset:64
	ds_read_b128 v[76:79], v76 offset:96
	s_waitcnt lgkmcnt(1)
	v_mfma_f32_32x32x16_bf16 v[32:47], v[72:75], v[120:123], v[32:47]
	v_or_b32_e32 v72, 48, v58
	v_or_b32_e32 v73, 32, v58
	v_add_u32_e32 v74, -16, v80
	v_sub_u32_e32 v80, v53, v72
	v_sub_u32_e32 v82, v54, v73
	v_cmp_lt_i32_e64 s[0:1], -1, v74
	s_waitcnt lgkmcnt(0)
	v_mfma_f32_32x32x16_bf16 v[32:47], v[76:79], v[124:127], v[32:47]
	s_nop 11
	v_mov_b32_e32 v156, v32
	v_pk_mul_f32 v[72:73], v[156:157], v[150:151]
	v_cvt_f32_u32_e32 v151, v74
	v_mov_b32_e32 v156, v33
	v_sub_f32_e32 v32, v72, v73
	v_sub_f32_e32 v32, v32, v67
	v_pk_mul_f32 v[72:73], v[156:157], v[150:151]
	v_cvt_f32_u32_e32 v151, v82
	v_mov_b32_e32 v156, v34
	v_sub_f32_e32 v33, v72, v73
	v_sub_f32_e32 v33, v33, v67
	v_pk_mul_f32 v[72:73], v[156:157], v[150:151]
	v_cvt_f32_u32_e32 v151, v80
	v_exp_f32_e32 v32, v32
	v_exp_f32_e32 v33, v33
	v_mov_b32_e32 v156, v35
	v_sub_f32_e32 v34, v72, v73
	v_pk_mul_f32 v[74:75], v[156:157], v[150:151]
	v_sub_f32_e32 v72, v34, v67
	v_pk_mul_f32 v[34:35], v[62:63], v[32:33]
	v_sub_f32_e32 v33, v74, v75
	v_sub_f32_e32 v33, v33, v67
	v_exp_f32_e32 v72, v72
	v_exp_f32_e32 v73, v33
	v_cndmask_b32_e64 v32, 0, v35, s[0:1]
	v_cmp_lt_i32_e64 s[0:1], -1, v81
	v_pk_mul_f32 v[72:73], v[62:63], v[72:73]
	s_nop 0
	v_cndmask_b32_e64 v34, 0, v34, s[0:1]
	v_cmp_lt_i32_e64 s[0:1], -1, v80
	v_add_f32_e32 v33, v34, v32
	s_nop 0
	v_cndmask_b32_e64 v35, 0, v73, s[0:1]
	v_cmp_lt_i32_e64 s[0:1], -1, v82
	s_nop 1
	v_mov_b32_dpp v74, v35 quad_perm:[1,0,3,2] row_mask:0xf bank_mask:0xf
	s_waitcnt lgkmcnt(0)
	v_add_f32_e32 v74, v35, v74
	v_cndmask_b32_e64 v72, 0, v72, s[0:1]
	v_add_f32_e32 v73, v72, v35
	v_add_f32_e32 v33, v33, v73
	s_nop 1
	v_mov_b32_dpp v73, v33 quad_perm:[1,0,3,2] row_mask:0xf bank_mask:0xf
	s_nop 1
	v_mov_b32_dpp v76, v74 quad_perm:[2,3,0,1] row_mask:0xf bank_mask:0xf
	s_waitcnt lgkmcnt(1)
	v_add_f32_e32 v73, v33, v73
	s_nop 1
	v_mov_b32_dpp v75, v73 quad_perm:[2,3,0,1] row_mask:0xf bank_mask:0xf
	v_mov_b32_e32 v33, v58
	s_and_saveexec_b64 s[0:1], s[6:7]
	s_waitcnt lgkmcnt(0)
	v_add_f32_e32 v73, v73, v75
	v_add_f32_e32 v74, v74, v76
	ds_write_b32 v70, v73
	ds_write_b32 v70, v74 offset:4100
.LBB0_1004:
	s_or_b64 exec, exec, s[0:1]
	v_or_b32_e32 v73, 64, v58
	v_sub_u32_e32 v73, v54, v73
	v_cvt_f32_u32_e32 v151, v73
	v_or_b32_e32 v74, 0x50, v33
	v_mov_b32_e32 v156, v36
	s_waitcnt lgkmcnt(1)
	v_sub_u32_e32 v76, v53, v74
	s_waitcnt lgkmcnt(0)
	v_pk_mul_f32 v[74:75], v[156:157], v[150:151]
	v_cvt_f32_u32_e32 v151, v76
	v_mov_b32_e32 v156, v37
	v_sub_f32_e32 v36, v74, v75
	v_sub_f32_e32 v36, v36, v67
	v_pk_mul_f32 v[74:75], v[156:157], v[150:151]
	v_exp_f32_e32 v36, v36
	v_sub_f32_e32 v37, v74, v75
	v_sub_f32_e32 v37, v37, v67
	v_exp_f32_e32 v37, v37
	v_or_b32_e32 v77, 0x60, v58
	v_sub_u32_e32 v77, v54, v77
	v_cvt_f32_u32_e32 v151, v77
	v_pk_mul_f32 v[74:75], v[62:63], v[36:37]
	v_or_b32_e32 v36, 0x70, v33
	v_sub_u32_e32 v78, v53, v36
	v_mov_b32_e32 v156, v38
	v_pk_mul_f32 v[36:37], v[156:157], v[150:151]
	v_cvt_f32_u32_e32 v151, v78
	v_sub_f32_e32 v36, v36, v37
	v_sub_f32_e32 v36, v36, v67
	v_mov_b32_e32 v156, v39
	v_exp_f32_e32 v38, v36
	v_pk_mul_f32 v[36:37], v[156:157], v[150:151]
	v_cmp_lt_i32_e64 s[0:1], -1, v76
	v_sub_f32_e32 v36, v36, v37
	v_sub_f32_e32 v36, v36, v67
	v_exp_f32_e32 v39, v36
	v_cndmask_b32_e64 v36, 0, v75, s[0:1]
	v_cmp_lt_i32_e64 s[0:1], -1, v73
	s_nop 1
	v_cndmask_b32_e64 v37, 0, v74, s[0:1]
	v_pk_mul_f32 v[74:75], v[62:63], v[38:39]
	v_cmp_lt_i32_e64 s[0:1], -1, v78
	s_nop 1
	v_cndmask_b32_e64 v38, 0, v75, s[0:1]
	v_cmp_lt_i32_e64 s[0:1], -1, v77
	s_nop 1
	v_mov_b32_dpp v75, v38 quad_perm:[1,0,3,2] row_mask:0xf bank_mask:0xf
	s_waitcnt lgkmcnt(0)
	v_add_f32_e32 v75, v38, v75
	v_cndmask_b32_e64 v39, 0, v74, s[0:1]
	v_add_f32_e32 v73, v39, v38
	v_add_f32_e32 v74, v37, v36
	v_add_f32_e32 v73, v74, v73
	s_nop 1
	v_mov_b32_dpp v74, v73 quad_perm:[1,0,3,2] row_mask:0xf bank_mask:0xf
	s_nop 1
	v_mov_b32_dpp v76, v75 quad_perm:[2,3,0,1] row_mask:0xf bank_mask:0xf
	s_waitcnt lgkmcnt(1)
	v_add_f32_e32 v73, v73, v74
	s_nop 1
	v_mov_b32_dpp v74, v73 quad_perm:[2,3,0,1] row_mask:0xf bank_mask:0xf
	s_and_saveexec_b64 s[0:1], s[6:7]
	s_waitcnt lgkmcnt(0)
	v_add_f32_e32 v73, v73, v74
	v_add_f32_e32 v75, v75, v76
	ds_write_b32 v70, v73 offset:4
	ds_write_b32 v70, v75 offset:4104
; DI float fexp2(float x) { return __builtin_amdgcn_exp2f(x); }
; DI void nsa_block(const bf16_t* P1, const bf16_t* VT1, const bf16_t* KSF, const bf16_t* KC, const bf16_t* VCT, bf16_t* O, const unsigned* kmx, int b, int g, int t0b, int wave, int lane, unsigned char* lds) {
;     ...
;         if (it >= lo_w && it < ntile) {
;         const int ib = 32 * it;
;         f32x16 s = qk_lds(B, qf, krow, hf);
; #pragma unroll
;         for (int j = 0; j < 16; ++j) { const int dist = t - 31 - 16 * (ib + 16 * (j >> 3) + 8 * hf + (j & 7)); s[j] = dist >= 0 ? fexp2(s[j] * C1 - slope2 * (float)dist - m) * inv : 0.f; }
; #pragma unroll
;         for (int q = 0; q < 4; ++q) {
;             float gsum = (s[4 * q] + s[4 * q + 1]) + (s[4 * q + 2] + s[4 * q + 3]), e = s[4 * q + 3];
;             gsum += __shfl_xor(gsum, 1); gsum += __shfl_xor(gsum, 2); e += __shfl_xor(e, 1); e += __shfl_xor(e, 2);
;             const int ssel = (ib >> 2) + 4 * (q >> 1) + 2 * hf + (q & 1);
;             if (hh == 0) { impA[tk * 128 + ssel] = gsum; if (ssel + 1 < 128) impB[tk * 128 + ssel + 1] = e; }
;         }
;         const bf16x8 p0 = pack8(s[0], s[1], s[2], s[3], s[4], s[5], s[6], s[7]), p1 = pack8(s[8], s[9], s[10], s[11], s[12], s[13], s[14], s[15]);
;         pv_lds(B, p0, p1, of0, of1, r, hf);
.LBB0_1006:
	s_or_b64 exec, exec, s[0:1]
	v_or_b32_e32 v73, 0x100, v58
	v_sub_u32_e32 v73, v54, v73
	v_cvt_f32_u32_e32 v151, v73
	s_waitcnt lgkmcnt(0)
	v_or_b32_e32 v74, 0x110, v33
	v_mov_b32_e32 v156, v40
	v_sub_u32_e32 v76, v53, v74
	v_pk_mul_f32 v[74:75], v[156:157], v[150:151]
	v_cvt_f32_u32_e32 v151, v76
	v_mov_b32_e32 v156, v41
	v_sub_f32_e32 v40, v74, v75
	v_sub_f32_e32 v40, v40, v67
	v_pk_mul_f32 v[74:75], v[156:157], v[150:151]
	v_exp_f32_e32 v40, v40
	v_sub_f32_e32 v41, v74, v75
	v_sub_f32_e32 v41, v41, v67
	v_exp_f32_e32 v41, v41
	v_or_b32_e32 v77, 0x120, v58
	v_sub_u32_e32 v77, v54, v77
	v_cvt_f32_u32_e32 v151, v77
	v_pk_mul_f32 v[74:75], v[62:63], v[40:41]
	v_or_b32_e32 v40, 0x130, v33
	v_sub_u32_e32 v78, v53, v40
	v_mov_b32_e32 v156, v42
	v_pk_mul_f32 v[40:41], v[156:157], v[150:151]
	v_cvt_f32_u32_e32 v151, v78
	v_sub_f32_e32 v40, v40, v41
	v_sub_f32_e32 v40, v40, v67
	v_mov_b32_e32 v156, v43
	v_exp_f32_e32 v42, v40
	v_pk_mul_f32 v[40:41], v[156:157], v[150:151]
	v_cmp_lt_i32_e64 s[0:1], -1, v76
	v_sub_f32_e32 v40, v40, v41
	v_sub_f32_e32 v40, v40, v67
	v_exp_f32_e32 v43, v40
	v_cndmask_b32_e64 v40, 0, v75, s[0:1]
	v_cmp_lt_i32_e64 s[0:1], -1, v73
	s_nop 1
	v_cndmask_b32_e64 v41, 0, v74, s[0:1]
	v_pk_mul_f32 v[74:75], v[62:63], v[42:43]
	v_cmp_lt_i32_e64 s[0:1], -1, v78
	s_nop 1
	v_cndmask_b32_e64 v42, 0, v75, s[0:1]
	v_cmp_lt_i32_e64 s[0:1], -1, v77
	s_nop 1
	v_mov_b32_dpp v75, v42 quad_perm:[1,0,3,2] row_mask:0xf bank_mask:0xf
	s_waitcnt lgkmcnt(0)
	v_add_f32_e32 v75, v42, v75
	v_cndmask_b32_e64 v43, 0, v74, s[0:1]
	v_add_f32_e32 v73, v43, v42
	v_add_f32_e32 v74, v41, v40
	v_add_f32_e32 v73, v74, v73
	s_nop 1
	v_mov_b32_dpp v74, v73 quad_perm:[1,0,3,2] row_mask:0xf bank_mask:0xf
	s_nop 1
	v_mov_b32_dpp v76, v75 quad_perm:[2,3,0,1] row_mask:0xf bank_mask:0xf
	s_waitcnt lgkmcnt(1)
	v_add_f32_e32 v73, v73, v74
	s_nop 1
	v_mov_b32_dpp v74, v73 quad_perm:[2,3,0,1] row_mask:0xf bank_mask:0xf
	s_and_saveexec_b64 s[0:1], s[6:7]
	s_waitcnt lgkmcnt(0)
	v_add_f32_e32 v73, v73, v74
	v_add_f32_e32 v75, v75, v76
	ds_write_b32 v70, v73 offset:16
	ds_write_b32 v70, v75 offset:4116
.LBB0_1008:
	s_or_b64 exec, exec, s[0:1]
	v_or_b32_e32 v73, 0x140, v58
	v_sub_u32_e32 v73, v54, v73
	v_cvt_f32_u32_e32 v151, v73
	s_waitcnt lgkmcnt(0)
	v_or_b32_e32 v74, 0x150, v33
	v_mov_b32_e32 v156, v44
	v_sub_u32_e32 v76, v53, v74
	v_pk_mul_f32 v[74:75], v[156:157], v[150:151]
	v_cvt_f32_u32_e32 v151, v76
	v_mov_b32_e32 v156, v45
	v_sub_f32_e32 v44, v74, v75
	v_or_b32_e32 v33, 0x170, v33
	v_pk_mul_f32 v[74:75], v[156:157], v[150:151]
	v_sub_u32_e32 v78, v53, v33
	v_sub_f32_e32 v45, v74, v75
	v_or_b32_e32 v74, 0x160, v58
	v_sub_u32_e32 v77, v54, v74
	v_cvt_f32_u32_e32 v151, v77
	v_mov_b32_e32 v156, v46
	v_sub_f32_e32 v44, v44, v67
	v_sub_f32_e32 v45, v45, v67
	v_pk_mul_f32 v[74:75], v[156:157], v[150:151]
	v_cvt_f32_u32_e32 v151, v78
	v_sub_f32_e32 v33, v74, v75
	v_mov_b32_e32 v156, v47
	v_sub_f32_e32 v33, v33, v67
	v_pk_mul_f32 v[74:75], v[156:157], v[150:151]
	v_exp_f32_e32 v44, v44
	v_exp_f32_e32 v45, v45
	v_exp_f32_e32 v46, v33
	v_sub_f32_e32 v33, v74, v75
	v_sub_f32_e32 v33, v33, v67
	v_exp_f32_e32 v47, v33
	v_pk_mul_f32 v[44:45], v[62:63], v[44:45]
	v_cmp_lt_i32_e64 s[0:1], -1, v76
	v_pk_mul_f32 v[46:47], v[62:63], v[46:47]
	s_nop 0
	v_cndmask_b32_e64 v33, 0, v45, s[0:1]
	v_cmp_lt_i32_e64 s[0:1], -1, v73
	s_nop 1
	v_cndmask_b32_e64 v44, 0, v44, s[0:1]
	v_cmp_lt_i32_e64 s[0:1], -1, v78
	v_add_f32_e32 v73, v44, v33
	s_nop 0
	v_cndmask_b32_e64 v45, 0, v47, s[0:1]
	v_cmp_lt_i32_e64 s[0:1], -1, v77
	s_nop 1
	v_mov_b32_dpp v76, v45 quad_perm:[1,0,3,2] row_mask:0xf bank_mask:0xf
	s_nop 0
	v_cndmask_b32_e64 v46, 0, v46, s[0:1]
	v_add_f32_e32 v47, v46, v45
	v_add_f32_e32 v47, v73, v47
	s_nop 1
	v_mov_b32_dpp v73, v47 quad_perm:[1,0,3,2] row_mask:0xf bank_mask:0xf
	s_waitcnt lgkmcnt(0)
	v_add_f32_e32 v74, v47, v73
	v_add_f32_e32 v47, v45, v76
	s_nop 1
	v_mov_b32_dpp v75, v74 quad_perm:[2,3,0,1] row_mask:0xf bank_mask:0xf
	s_nop 1
	v_mov_b32_dpp v73, v47 quad_perm:[2,3,0,1] row_mask:0xf bank_mask:0xf
	s_and_saveexec_b64 s[10:11], s[6:7]
	s_waitcnt lgkmcnt(1)
	v_add_f32_e32 v74, v74, v75
	v_cmp_ne_u32_e64 s[0:1], 0, v69
	ds_write_b32 v70, v74 offset:20
	s_and_b64 exec, exec, s[0:1]
	s_cbranch_execz .LBB0_1011
	s_waitcnt lgkmcnt(1)
	v_add_f32_e32 v47, v47, v73
	ds_write_b32 v70, v47 offset:4120

; DI float fexp2(float x) { return __builtin_amdgcn_exp2f(x); }
; DI void nsa_block(const bf16_t* P1, const bf16_t* VT1, const bf16_t* KSF, const bf16_t* KC, const bf16_t* VCT, bf16_t* O, const unsigned* kmx, int b, int g, int t0b, int wave, int lane, unsigned char* lds) {
;     ...
;         if (it >= lo_w && it < ntile) {
;         const int ib = 32 * it;
;         f32x16 s = qk_lds(B, qf, krow, hf);
; #pragma unroll
;         for (int j = 0; j < 16; ++j) { const int dist = t - 31 - 16 * (ib + 16 * (j >> 3) + 8 * hf + (j & 7)); s[j] = dist >= 0 ? fexp2(s[j] * C1 - slope2 * (float)dist - m) * inv : 0.f; }
; #pragma unroll
;         for (int q = 0; q < 4; ++q) {
;             float gsum = (s[4 * q] + s[4 * q + 1]) + (s[4 * q + 2] + s[4 * q + 3]), e = s[4 * q + 3];
;             gsum += __shfl_xor(gsum, 1); gsum += __shfl_xor(gsum, 2); e += __shfl_xor(e, 1); e += __shfl_xor(e, 2);
;             const int ssel = (ib >> 2) + 4 * (q >> 1) + 2 * hf + (q & 1);
;             if (hh == 0) { impA[tk * 128 + ssel] = gsum; if (ssel + 1 < 128) impB[tk * 128 + ssel + 1] = e; }
;         }
;         const bf16x8 p0 = pack8(s[0], s[1], s[2], s[3], s[4], s[5], s[6], s[7]), p1 = pack8(s[8], s[9], s[10], s[11], s[12], s[13], s[14], s[15]);
;         pv_lds(B, p0, p1, of0, of1, r, hf);
;         }
.LBB0_1016:
	s_nop 0
	s_nop 0
	s_nop 0
	s_nop 0
	s_or_b64 exec, exec, s[14:15]
